# SSD staging: fast path without row-validity selects for full chunks
# baseline (speedup 1.0000x reference)
; #define LAS __attribute__((address_space(3)))
; __device__ __forceinline__ unsigned f2bf(float f) { return pk2(f, 0.f) & 0xffffu; }
; __device__ __forceinline__ float fexp(float x) { return __builtin_amdgcn_exp2f(x * 1.4426950408889634f); }
; __device__ __forceinline__ void ssd_item(const Params& P, LAS unsigned char* lds, int item, int tid, int wave, int lane) {
;     ...
;         const int p0 = 128 * c, nvalid = (LL - p0) < 128 ? (LL - p0) : 128;
;         LAS float* ACS = (LAS float*)(lds + S_ACS) + (c & 1) * 128; LAS float* DTV = (LAS float*)(lds + S_DTV) + (c & 1) * 128;
; #pragma unroll
;         for (int k = 0; k < 8; ++k) { const int br = brow0 + 16 * k;
;             u32x4 v = pbc[k]; if (br >= nvalid) v = (u32x4){0u, 0u, 0u, 0u};
;             *(LAS u32x4*)(lds + (bsel ? S_CC : S_BC) + br * LP + boct * 16) = v; }
;         {
;             const float aend = ACS[127];
; #pragma unroll
;             for (int q = 0; q < 2; ++q) { const int s = xrow0 + 64 * q; const bool sv = s < nvalid;
;                 const float dtv = DTV[s], dd = fexp(aend - ACS[s]);
;                 const unsigned w4[4] = {pxv[q].x, pxv[q].y, pxv[q].z, pxv[q].w};
;                 const int sofs = (((s >> 3) ^ xoct) << 4) + (s & 7) * 2;
; #pragma unroll
;                 for (int j = 0; j < 8; ++j) { float x = (j & 1) ? bfhi(w4[j >> 1]) : bflo(w4[j >> 1]); x = sv ? x : 0.f; const int p = xoct * 8 + j;
;                     const float xd = x * dtv;
;                     *(LAS unsigned short*)(lds + S_XDTT + p * LP + sofs) = (unsigned short)f2bf(xd);
;                     *(LAS unsigned short*)(lds + S_XDDT + p * LP + sofs) = (unsigned short)f2bf(xd * dd); } }
;         }
;         __syncthreads();
;         u32x2 zc[4], xc[4];
;         {
;             const int zb = __builtin_amdgcn_readfirstlane((int)(((unsigned)rowbase + p0 + wave * 16) * LDP * 2u));
; #pragma unroll
;             for (int i = 0; i < 4; ++i) { zc[i] = __builtin_bit_cast(u32x2, __builtin_amdgcn_raw_buffer_load_b64(prs, zvoff, zb + i * (LDP * 2), 2));
;                                           xc[i] = __builtin_bit_cast(u32x2, __builtin_amdgcn_raw_buffer_load_b64(prs, xvoff, zb + i * (LDP * 2), 2)); }
.LBB0_318:
	s_waitcnt vmcnt(4)
	s_lshl_b32 s98, s17, 7
	s_add_i32 s98, s98, s16
	s_mul_i32 s98, s98, 0x2c20
	s_add_i32 s99, s98, 0x2c20
	s_add_i32 s100, s98, 0x5840
	s_add_i32 s101, s98, 0x8460
	buffer_load_dwordx2 v[160:161], v214, s[84:87], s98 offen nt
	buffer_load_dwordx2 v[156:157], v214, s[84:87], s99 offen nt
	buffer_load_dwordx2 v[150:151], v214, s[84:87], s100 offen nt
	buffer_load_dwordx2 v[144:145], v214, s[84:87], s101 offen nt
	buffer_load_dwordx2 v[158:159], v213, s[84:87], s98 offen nt
	buffer_load_dwordx2 v[154:155], v213, s[84:87], s99 offen nt
	buffer_load_dwordx2 v[148:149], v213, s[84:87], s100 offen nt
	buffer_load_dwordx2 v[146:147], v213, s[84:87], s101 offen nt
	s_cmp_eq_u32 s17, 32
	s_cbranch_scc1 .Lssd_stage_slow
	s_lshl_b32 s6, s17, 7
	s_sub_i32 s7, 0x1010, s6
	s_min_u32 s19, s7, 0x80
	s_lshl_b32 s7, s17, 9
	s_and_b32 s7, s7, 0x200
	ds_write_b128 v188, v[48:51]
	s_add_i32 s21, s7, 0
	ds_write_b128 v188, v[52:55] offset:4352
	s_add_i32 s21, s21, 0x26400
	ds_write_b128 v188, v[56:59] offset:8704
	v_lshlrev_b32_e32 v21, 16, v80
	ds_write_b128 v188, v[60:63] offset:13056
	s_add_i32 s20, s16, s6
	ds_write_b128 v188, v[64:67] offset:17408
	s_mul_i32 s6, s20, 0x2c20
	ds_write_b128 v188, v[68:71] offset:21760
	s_add_i32 s18, s6, 0x5840
	ds_write_b128 v188, v[72:75] offset:26112
	s_add_i32 s74, s6, 0x8460
	ds_write_b128 v188, v[76:79] offset:30464
	v_mov_b32_e32 v16, s21
	ds_read_b32 v20, v16 offset:508
	v_lshl_add_u32 v16, v122, 2, s21
	ds_read2st64_b32 v[16:17], v16 offset1:1
	v_add_u32_e32 v18, s7, v179
	ds_read2st64_b32 v[18:19], v18 offset1:1
	s_add_i32 s7, s6, 0x2c20
	s_waitcnt lgkmcnt(1)
	v_sub_f32_e32 v16, v20, v16
	v_mul_f32_e32 v16, 0x3fb8aa3b, v16
	v_exp_f32_e32 v16, v16
	s_waitcnt lgkmcnt(0)
	v_mul_f32_e32 v21, v21, v18
	v_cvt_pk_bf16_f32 v22, v21, s0
	v_mul_f32_e32 v21, v21, v16
	v_cvt_pk_bf16_f32 v21, v21, s0
	ds_write_b16 v190, v21
	v_and_b32_e32 v21, 0xffff0000, v80
	v_mul_f32_e32 v21, v21, v18
	ds_write_b16 v189, v22
	v_cvt_pk_bf16_f32 v22, v21, s0
	v_mul_f32_e32 v21, v21, v16
	v_cvt_pk_bf16_f32 v21, v21, s0
	ds_write_b16 v190, v21 offset:272
	v_lshlrev_b32_e32 v21, 16, v81
	v_mul_f32_e32 v21, v21, v18
	ds_write_b16 v189, v22 offset:272
	v_cvt_pk_bf16_f32 v22, v21, s0
	v_mul_f32_e32 v21, v21, v16
	v_cvt_pk_bf16_f32 v21, v21, s0
	ds_write_b16 v190, v21 offset:544
	v_and_b32_e32 v21, 0xffff0000, v81
	v_mul_f32_e32 v21, v21, v18
	ds_write_b16 v189, v22 offset:544
	v_cvt_pk_bf16_f32 v22, v21, s0
	v_mul_f32_e32 v21, v21, v16
	v_cvt_pk_bf16_f32 v21, v21, s0
	ds_write_b16 v190, v21 offset:816
	v_lshlrev_b32_e32 v21, 16, v82
	v_mul_f32_e32 v21, v21, v18
	ds_write_b16 v189, v22 offset:816
	v_cvt_pk_bf16_f32 v22, v21, s0
	v_mul_f32_e32 v21, v21, v16
	v_cvt_pk_bf16_f32 v21, v21, s0
	ds_write_b16 v190, v21 offset:1088
	v_and_b32_e32 v21, 0xffff0000, v82
	v_mul_f32_e32 v21, v21, v18
	ds_write_b16 v189, v22 offset:1088
	v_cvt_pk_bf16_f32 v22, v21, s0
	v_mul_f32_e32 v21, v21, v16
	v_cvt_pk_bf16_f32 v21, v21, s0
	ds_write_b16 v190, v21 offset:1360
	v_lshlrev_b32_e32 v21, 16, v83
	v_mul_f32_e32 v21, v21, v18
	ds_write_b16 v189, v22 offset:1360
	v_cvt_pk_bf16_f32 v22, v21, s0
	v_mul_f32_e32 v21, v21, v16
	v_cvt_pk_bf16_f32 v21, v21, s0
	ds_write_b16 v190, v21 offset:1632
	v_and_b32_e32 v21, 0xffff0000, v83
	v_mul_f32_e32 v18, v21, v18
	v_mul_f32_e32 v16, v18, v16
	v_cvt_pk_bf16_f32 v16, v16, s0
	ds_write_b16 v190, v16 offset:1904
	v_sub_f32_e32 v16, v20, v17
	v_mul_f32_e32 v16, 0x3fb8aa3b, v16
	v_exp_f32_e32 v16, v16
	v_lshlrev_b32_e32 v17, 16, v84
	v_cvt_pk_bf16_f32 v21, v18, s0
	ds_write_b16 v189, v22 offset:1632
	v_mul_f32_e32 v17, v17, v19
	v_cvt_pk_bf16_f32 v18, v17, s0
	v_mul_f32_e32 v17, v17, v16
	v_cvt_pk_bf16_f32 v17, v17, s0
	ds_write_b16 v192, v17
	v_and_b32_e32 v17, 0xffff0000, v84
	v_mul_f32_e32 v17, v17, v19
	ds_write_b16 v189, v21 offset:1904
	ds_write_b16 v191, v18
	v_cvt_pk_bf16_f32 v18, v17, s0
	v_mul_f32_e32 v17, v17, v16
	v_cvt_pk_bf16_f32 v17, v17, s0
	ds_write_b16 v192, v17 offset:272
	v_lshlrev_b32_e32 v17, 16, v85
	v_mul_f32_e32 v17, v17, v19
	ds_write_b16 v191, v18 offset:272
	v_cvt_pk_bf16_f32 v18, v17, s0
	v_mul_f32_e32 v17, v17, v16
	v_cvt_pk_bf16_f32 v17, v17, s0
	ds_write_b16 v192, v17 offset:544
	v_and_b32_e32 v17, 0xffff0000, v85
	v_mul_f32_e32 v17, v17, v19
	ds_write_b16 v191, v18 offset:544
	v_cvt_pk_bf16_f32 v18, v17, s0
	v_mul_f32_e32 v17, v17, v16
	v_cvt_pk_bf16_f32 v17, v17, s0
	ds_write_b16 v192, v17 offset:816
	v_lshlrev_b32_e32 v17, 16, v86
	v_mul_f32_e32 v17, v17, v19
	ds_write_b16 v191, v18 offset:816
	v_cvt_pk_bf16_f32 v18, v17, s0
	v_mul_f32_e32 v17, v17, v16
	v_cvt_pk_bf16_f32 v17, v17, s0
	ds_write_b16 v192, v17 offset:1088
	v_and_b32_e32 v17, 0xffff0000, v86
	v_mul_f32_e32 v17, v17, v19
	ds_write_b16 v191, v18 offset:1088
	v_cvt_pk_bf16_f32 v18, v17, s0
	v_mul_f32_e32 v17, v17, v16
	v_cvt_pk_bf16_f32 v17, v17, s0
	ds_write_b16 v192, v17 offset:1360
	v_lshlrev_b32_e32 v17, 16, v87
	v_mul_f32_e32 v17, v17, v19
	ds_write_b16 v191, v18 offset:1360
	v_cvt_pk_bf16_f32 v18, v17, s0
	v_mul_f32_e32 v17, v17, v16
	v_cvt_pk_bf16_f32 v17, v17, s0
	ds_write_b16 v192, v17 offset:1632
	v_and_b32_e32 v17, 0xffff0000, v87
	v_mul_f32_e32 v17, v17, v19
	v_mul_f32_e32 v16, v17, v16
	ds_write_b16 v191, v18 offset:1632
	v_cvt_pk_bf16_f32 v18, v17, s0
	v_cvt_pk_bf16_f32 v16, v16, s0
	ds_write_b16 v191, v18 offset:1904
	ds_write_b16 v192, v16 offset:1904
	s_branch .Lssd_stage_join
; #define LAS __attribute__((address_space(3)))
; __device__ __forceinline__ unsigned f2bf(float f) { return pk2(f, 0.f) & 0xffffu; }
; __device__ __forceinline__ float fexp(float x) { return __builtin_amdgcn_exp2f(x * 1.4426950408889634f); }
; __device__ __forceinline__ void ssd_item(const Params& P, LAS unsigned char* lds, int item, int tid, int wave, int lane) {
;     ...
;         const int p0 = 128 * c, nvalid = (LL - p0) < 128 ? (LL - p0) : 128;
;         LAS float* ACS = (LAS float*)(lds + S_ACS) + (c & 1) * 128; LAS float* DTV = (LAS float*)(lds + S_DTV) + (c & 1) * 128;
; #pragma unroll
;         for (int k = 0; k < 8; ++k) { const int br = brow0 + 16 * k;
;             u32x4 v = pbc[k]; if (br >= nvalid) v = (u32x4){0u, 0u, 0u, 0u};
;             *(LAS u32x4*)(lds + (bsel ? S_CC : S_BC) + br * LP + boct * 16) = v; }
;         {
;             const float aend = ACS[127];
; #pragma unroll
;             for (int q = 0; q < 2; ++q) { const int s = xrow0 + 64 * q; const bool sv = s < nvalid;
;                 const float dtv = DTV[s], dd = fexp(aend - ACS[s]);
;                 const unsigned w4[4] = {pxv[q].x, pxv[q].y, pxv[q].z, pxv[q].w};
;                 const int sofs = (((s >> 3) ^ xoct) << 4) + (s & 7) * 2;
; #pragma unroll
;                 for (int j = 0; j < 8; ++j) { float x = (j & 1) ? bfhi(w4[j >> 1]) : bflo(w4[j >> 1]); x = sv ? x : 0.f; const int p = xoct * 8 + j;
;                     const float xd = x * dtv;
;                     *(LAS unsigned short*)(lds + S_XDTT + p * LP + sofs) = (unsigned short)f2bf(xd);
;                     *(LAS unsigned short*)(lds + S_XDDT + p * LP + sofs) = (unsigned short)f2bf(xd * dd); } }
;         }
;         __syncthreads();
;     ...
;         if (c + 1 < 33) SSD_LOAD(c + 1);
.Lssd_stage_slow:
	s_lshl_b32 s6, s17, 7
	s_sub_i32 s7, 0x1010, s6
	s_min_u32 s19, s7, 0x80
	v_cmp_gt_u32_e32 vcc, s19, v104
	s_lshl_b32 s7, s17, 9
	s_and_b32 s7, s7, 0x200
	v_cndmask_b32_e32 v19, 0, v51, vcc
	v_cndmask_b32_e32 v18, 0, v50, vcc
	v_cndmask_b32_e32 v17, 0, v49, vcc
	v_cndmask_b32_e32 v16, 0, v48, vcc
	v_cmp_gt_u32_e32 vcc, s19, v108
	ds_write_b128 v188, v[16:19]
	s_add_i32 s21, s7, 0
	v_cndmask_b32_e32 v19, 0, v55, vcc
	v_cndmask_b32_e32 v18, 0, v54, vcc
	v_cndmask_b32_e32 v17, 0, v53, vcc
	v_cndmask_b32_e32 v16, 0, v52, vcc
	v_cmp_gt_u32_e32 vcc, s19, v110
	ds_write_b128 v188, v[16:19] offset:4352
	s_add_i32 s21, s21, 0x26400
	v_cndmask_b32_e32 v19, 0, v59, vcc
	v_cndmask_b32_e32 v18, 0, v58, vcc
	v_cndmask_b32_e32 v17, 0, v57, vcc
	v_cndmask_b32_e32 v16, 0, v56, vcc
	v_cmp_gt_u32_e32 vcc, s19, v112
	ds_write_b128 v188, v[16:19] offset:8704
	v_lshlrev_b32_e32 v21, 16, v80
	v_cndmask_b32_e32 v19, 0, v63, vcc
	v_cndmask_b32_e32 v18, 0, v62, vcc
	v_cndmask_b32_e32 v17, 0, v61, vcc
	v_cndmask_b32_e32 v16, 0, v60, vcc
	v_cmp_gt_u32_e32 vcc, s19, v114
	ds_write_b128 v188, v[16:19] offset:13056
	s_add_i32 s20, s16, s6
	v_cndmask_b32_e32 v19, 0, v67, vcc
	v_cndmask_b32_e32 v18, 0, v66, vcc
	v_cndmask_b32_e32 v17, 0, v65, vcc
	v_cndmask_b32_e32 v16, 0, v64, vcc
	v_cmp_gt_u32_e32 vcc, s19, v116
	ds_write_b128 v188, v[16:19] offset:17408
	s_mul_i32 s6, s20, 0x2c20
	v_cndmask_b32_e32 v19, 0, v71, vcc
	v_cndmask_b32_e32 v18, 0, v70, vcc
	v_cndmask_b32_e32 v17, 0, v69, vcc
	v_cndmask_b32_e32 v16, 0, v68, vcc
	v_cmp_gt_u32_e32 vcc, s19, v118
	ds_write_b128 v188, v[16:19] offset:21760
	s_add_i32 s18, s6, 0x5840
	v_cndmask_b32_e32 v19, 0, v75, vcc
	v_cndmask_b32_e32 v18, 0, v74, vcc
	v_cndmask_b32_e32 v17, 0, v73, vcc
	v_cndmask_b32_e32 v16, 0, v72, vcc
	v_cmp_gt_u32_e32 vcc, s19, v168
	ds_write_b128 v188, v[16:19] offset:26112
	s_add_i32 s74, s6, 0x8460
	v_cndmask_b32_e32 v19, 0, v79, vcc
	v_cndmask_b32_e32 v18, 0, v78, vcc
	v_cndmask_b32_e32 v17, 0, v77, vcc
	v_cndmask_b32_e32 v16, 0, v76, vcc
	ds_write_b128 v188, v[16:19] offset:30464
	v_mov_b32_e32 v16, s21
	ds_read_b32 v20, v16 offset:508
	v_lshl_add_u32 v16, v122, 2, s21
	ds_read2st64_b32 v[16:17], v16 offset1:1
	v_add_u32_e32 v18, s7, v179
	ds_read2st64_b32 v[18:19], v18 offset1:1
	v_cmp_gt_u32_e32 vcc, s19, v122
	s_add_i32 s7, s6, 0x2c20
	s_waitcnt lgkmcnt(1)
	v_sub_f32_e32 v16, v20, v16
	v_mul_f32_e32 v16, 0x3fb8aa3b, v16
	v_exp_f32_e32 v16, v16
	v_cndmask_b32_e32 v21, 0, v21, vcc
	s_waitcnt lgkmcnt(0)
	v_mul_f32_e32 v21, v21, v18
	v_cvt_pk_bf16_f32 v22, v21, s0
	v_mul_f32_e32 v21, v21, v16
	v_cvt_pk_bf16_f32 v21, v21, s0
	ds_write_b16 v190, v21
	v_and_b32_e32 v21, 0xffff0000, v80
	v_cndmask_b32_e32 v21, 0, v21, vcc
	v_mul_f32_e32 v21, v21, v18
	ds_write_b16 v189, v22
	v_cvt_pk_bf16_f32 v22, v21, s0
	v_mul_f32_e32 v21, v21, v16
	v_cvt_pk_bf16_f32 v21, v21, s0
	ds_write_b16 v190, v21 offset:272
	v_lshlrev_b32_e32 v21, 16, v81
	v_cndmask_b32_e32 v21, 0, v21, vcc
	v_mul_f32_e32 v21, v21, v18
	ds_write_b16 v189, v22 offset:272
	v_cvt_pk_bf16_f32 v22, v21, s0
	v_mul_f32_e32 v21, v21, v16
	v_cvt_pk_bf16_f32 v21, v21, s0
	ds_write_b16 v190, v21 offset:544
	v_and_b32_e32 v21, 0xffff0000, v81
	v_cndmask_b32_e32 v21, 0, v21, vcc
	v_mul_f32_e32 v21, v21, v18
	ds_write_b16 v189, v22 offset:544
	v_cvt_pk_bf16_f32 v22, v21, s0
	v_mul_f32_e32 v21, v21, v16
	v_cvt_pk_bf16_f32 v21, v21, s0
	ds_write_b16 v190, v21 offset:816
	v_lshlrev_b32_e32 v21, 16, v82
	v_cndmask_b32_e32 v21, 0, v21, vcc
	v_mul_f32_e32 v21, v21, v18
	ds_write_b16 v189, v22 offset:816
	v_cvt_pk_bf16_f32 v22, v21, s0
	v_mul_f32_e32 v21, v21, v16
	v_cvt_pk_bf16_f32 v21, v21, s0
	ds_write_b16 v190, v21 offset:1088
	v_and_b32_e32 v21, 0xffff0000, v82
	v_cndmask_b32_e32 v21, 0, v21, vcc
	v_mul_f32_e32 v21, v21, v18
	ds_write_b16 v189, v22 offset:1088
	v_cvt_pk_bf16_f32 v22, v21, s0
	v_mul_f32_e32 v21, v21, v16
	v_cvt_pk_bf16_f32 v21, v21, s0
	ds_write_b16 v190, v21 offset:1360
	v_lshlrev_b32_e32 v21, 16, v83
	v_cndmask_b32_e32 v21, 0, v21, vcc
	v_mul_f32_e32 v21, v21, v18
	ds_write_b16 v189, v22 offset:1360
	v_cvt_pk_bf16_f32 v22, v21, s0
	v_mul_f32_e32 v21, v21, v16
	v_cvt_pk_bf16_f32 v21, v21, s0
	ds_write_b16 v190, v21 offset:1632
	v_and_b32_e32 v21, 0xffff0000, v83
	v_cndmask_b32_e32 v21, 0, v21, vcc
	v_mul_f32_e32 v18, v21, v18
	v_mul_f32_e32 v16, v18, v16
	v_cvt_pk_bf16_f32 v16, v16, s0
	ds_write_b16 v190, v16 offset:1904
	v_sub_f32_e32 v16, v20, v17
	v_mul_f32_e32 v16, 0x3fb8aa3b, v16
	v_exp_f32_e32 v16, v16
	v_lshlrev_b32_e32 v17, 16, v84
	v_cmp_gt_u32_e32 vcc, s19, v169
	v_cvt_pk_bf16_f32 v21, v18, s0
	ds_write_b16 v189, v22 offset:1632
	v_cndmask_b32_e32 v17, 0, v17, vcc
	v_mul_f32_e32 v17, v17, v19
	v_cvt_pk_bf16_f32 v18, v17, s0
	v_mul_f32_e32 v17, v17, v16
	v_cvt_pk_bf16_f32 v17, v17, s0
	ds_write_b16 v192, v17
	v_and_b32_e32 v17, 0xffff0000, v84
	v_cndmask_b32_e32 v17, 0, v17, vcc
	v_mul_f32_e32 v17, v17, v19
	ds_write_b16 v189, v21 offset:1904
	ds_write_b16 v191, v18
	v_cvt_pk_bf16_f32 v18, v17, s0
	v_mul_f32_e32 v17, v17, v16
	v_cvt_pk_bf16_f32 v17, v17, s0
	ds_write_b16 v192, v17 offset:272
	v_lshlrev_b32_e32 v17, 16, v85
	v_cndmask_b32_e32 v17, 0, v17, vcc
	v_mul_f32_e32 v17, v17, v19
	ds_write_b16 v191, v18 offset:272
	v_cvt_pk_bf16_f32 v18, v17, s0
	v_mul_f32_e32 v17, v17, v16
	v_cvt_pk_bf16_f32 v17, v17, s0
	ds_write_b16 v192, v17 offset:544
	v_and_b32_e32 v17, 0xffff0000, v85
	v_cndmask_b32_e32 v17, 0, v17, vcc
	v_mul_f32_e32 v17, v17, v19
	ds_write_b16 v191, v18 offset:544
	v_cvt_pk_bf16_f32 v18, v17, s0
	v_mul_f32_e32 v17, v17, v16
	v_cvt_pk_bf16_f32 v17, v17, s0
	ds_write_b16 v192, v17 offset:816
	v_lshlrev_b32_e32 v17, 16, v86
	v_cndmask_b32_e32 v17, 0, v17, vcc
	v_mul_f32_e32 v17, v17, v19
	ds_write_b16 v191, v18 offset:816
	v_cvt_pk_bf16_f32 v18, v17, s0
	v_mul_f32_e32 v17, v17, v16
	v_cvt_pk_bf16_f32 v17, v17, s0
	ds_write_b16 v192, v17 offset:1088
	v_and_b32_e32 v17, 0xffff0000, v86
	v_cndmask_b32_e32 v17, 0, v17, vcc
	v_mul_f32_e32 v17, v17, v19
	ds_write_b16 v191, v18 offset:1088
	v_cvt_pk_bf16_f32 v18, v17, s0
	v_mul_f32_e32 v17, v17, v16
	v_cvt_pk_bf16_f32 v17, v17, s0
	ds_write_b16 v192, v17 offset:1360
	v_lshlrev_b32_e32 v17, 16, v87
	v_cndmask_b32_e32 v17, 0, v17, vcc
	v_mul_f32_e32 v17, v17, v19
	ds_write_b16 v191, v18 offset:1360
	v_cvt_pk_bf16_f32 v18, v17, s0
	v_mul_f32_e32 v17, v17, v16
	v_cvt_pk_bf16_f32 v17, v17, s0
	ds_write_b16 v192, v17 offset:1632
	v_and_b32_e32 v17, 0xffff0000, v87
	v_cndmask_b32_e32 v17, 0, v17, vcc
	v_mul_f32_e32 v17, v17, v19
	v_mul_f32_e32 v16, v17, v16
	ds_write_b16 v191, v18 offset:1632
	v_cvt_pk_bf16_f32 v18, v17, s0
	v_cvt_pk_bf16_f32 v16, v16, s0
	ds_write_b16 v191, v18 offset:1904
	ds_write_b16 v192, v16 offset:1904
.Lssd_stage_join:
	s_waitcnt lgkmcnt(0)
	s_barrier
	s_add_i32 s18, s17, 1
	s_cmp_eq_u32 s17, 32
	s_cselect_b64 s[6:7], -1, 0
	s_and_b64 vcc, exec, s[6:7]
	s_cbranch_vccnz .LBB0_321
